# loop-edge trim: dead a3 pointer arithmetic removed from the FFN-up K loop and its peeled first iteration (SA(1,0) is staged from a1 since the rebalance)
# speedup vs baseline: 1.0024x; 1.0024x over previous
.LBB0_739:
	s_ashr_i32 s59, s58, 31
	s_lshl_b64 s[18:19], s[58:59], 19
	s_add_u32 s60, s16, s18
	s_addc_u32 s61, s33, s19
	s_and_b64 s[18:19], s[6:7], exec
	s_cselect_b32 s59, s61, s67
	s_cselect_b32 s81, s60, s66
	s_ashr_i32 s31, s30, 31
	s_lshl_b64 s[18:19], s[30:31], 19
	s_add_u32 s62, s5, s18
	s_addc_u32 s63, s46, s19
	s_and_b64 s[18:19], s[6:7], exec
	s_cselect_b32 s31, s63, s39
	s_cselect_b32 s82, s62, s38
	s_add_u32 s83, s38, 0x100
	s_addc_u32 s84, s39, 0
	s_mov_b32 s85, -2
	s_lshl_b32 s18, s64, 8
	s_add_i32 s18, s18, s75
	v_and_or_b32 v252, v217, 15, s18
	v_bfe_u32 v253, v217, 4, 2
	v_lshlrev_b32_e32 v252, 6, v252
	v_lshl_add_u32 v252, v253, 4, v252
	v_mov_b32_e32 v253, 0
	v_mov_b64_e32 v[184:185], 0x2000
	v_lshl_add_u64 v[252:253], s[10:11], 0, v[252:253]
	v_lshl_add_u64 v[184:185], v[252:253], 0, v[184:185]
	s_add_u32 s18, s66, 0x80
	s_addc_u32 s19, s67, 0
	s_add_u32 s66, s66, 0x100
	s_addc_u32 s67, s67, 0
	s_cmp_eq_u32 s85, 12
	s_cselect_b32 s42, s81, s66
	s_cselect_b32 s43, s59, s67
	s_cselect_b32 s45, s31, s84
	s_cselect_b32 s44, s82, s83
	s_add_u32 s68, s44, 0x80
	s_addc_u32 s69, s45, 0
	s_add_i32 s35, 0, 0x10000
	s_add_i32 s49, 0, 0x14000
	v_add_u32_e32 v96, s35, v151
	v_add_u32_e32 v150, s49, v151
	ds_read_b128 v[138:141], v96
	ds_read_b128 v[142:145], v96 offset:1024
	ds_read_b128 v[146:149], v96 offset:2048
	ds_read_b128 v[156:159], v96 offset:3072
	ds_read_b128 v[160:163], v150
	ds_read_b128 v[164:167], v150 offset:1024
	ds_read_b128 v[168:171], v150 offset:2048
	ds_read_b128 v[172:175], v150 offset:3072
	s_mov_b32 m0, s77
	ds_read_b128 v[176:179], v155
	ds_read_b128 v[180:183], v155 offset:1024
	ds_read_b128 v[190:193], v155 offset:2048
	ds_read_b128 v[194:197], v155 offset:3072
	ds_read_b128 v[198:201], v155 offset:4096
	ds_read_b128 v[202:205], v155 offset:5120
	ds_read_b128 v[206:209], v155 offset:6144
	ds_read_b128 v[210:213], v155 offset:7168
	global_load_lds_dwordx4 v136, s[18:19]
	s_mov_b32 m0, s78
	s_nop 0
	global_load_lds_dwordx4 v132, s[18:19]
	s_add_u32 s18, s18, 0x40000
	s_addc_u32 s19, s19, 0
	s_add_i32 m0, s65, 0xc000
	s_nop 0
	global_load_lds_dwordx4 v136, s[18:19]
	s_add_i32 m0, s65, 0xe000
	s_nop 0
	global_load_lds_dwordx4 v132, s[18:19]
	s_waitcnt vmcnt(8)
	s_waitcnt lgkmcnt(0)
	s_barrier
	s_setprio 1
	s_waitcnt lgkmcnt(0)
	v_mfma_f32_16x16x32_bf16 v[126:129], v[138:141], v[176:179], 0
	v_mfma_f32_16x16x32_bf16 v[118:121], v[146:149], v[176:179], 0
	v_mfma_f32_16x16x32_bf16 v[110:113], v[138:141], v[190:193], 0
	v_mfma_f32_16x16x32_bf16 v[102:105], v[146:149], v[190:193], 0
	v_mfma_f32_16x16x32_bf16 v[92:95], v[138:141], v[198:201], 0
	v_mfma_f32_16x16x32_bf16 v[84:87], v[146:149], v[198:201], 0
	v_mfma_f32_16x16x32_bf16 v[76:79], v[138:141], v[206:209], 0
	v_mfma_f32_16x16x32_bf16 v[68:71], v[146:149], v[206:209], 0
	v_mfma_f32_16x16x32_bf16 v[126:129], v[142:145], v[180:183], v[126:129]
	v_mfma_f32_16x16x32_bf16 v[118:121], v[156:159], v[180:183], v[118:121]
	v_mfma_f32_16x16x32_bf16 v[110:113], v[142:145], v[194:197], v[110:113]
	v_mfma_f32_16x16x32_bf16 v[102:105], v[156:159], v[194:197], v[102:105]
	v_mfma_f32_16x16x32_bf16 v[92:95], v[142:145], v[202:205], v[92:95]
	v_mfma_f32_16x16x32_bf16 v[84:87], v[156:159], v[202:205], v[84:87]
	v_mfma_f32_16x16x32_bf16 v[76:79], v[142:145], v[210:213], v[76:79]
	v_mfma_f32_16x16x32_bf16 v[68:71], v[156:159], v[210:213], v[68:71]
	v_mfma_f32_16x16x32_bf16 v[122:125], v[160:163], v[176:179], 0
	v_mfma_f32_16x16x32_bf16 v[114:117], v[168:171], v[176:179], 0
	v_mfma_f32_16x16x32_bf16 v[106:109], v[160:163], v[190:193], 0
	v_mfma_f32_16x16x32_bf16 v[98:101], v[168:171], v[190:193], 0
	v_mfma_f32_16x16x32_bf16 v[88:91], v[160:163], v[198:201], 0
	v_mfma_f32_16x16x32_bf16 v[80:83], v[168:171], v[198:201], 0
	v_mfma_f32_16x16x32_bf16 v[72:75], v[160:163], v[206:209], 0
	v_mfma_f32_16x16x32_bf16 v[64:67], v[168:171], v[206:209], 0
	v_mfma_f32_16x16x32_bf16 v[122:125], v[164:167], v[180:183], v[122:125]
	v_mfma_f32_16x16x32_bf16 v[114:117], v[172:175], v[180:183], v[114:117]
	v_mfma_f32_16x16x32_bf16 v[106:109], v[164:167], v[194:197], v[106:109]
	v_mfma_f32_16x16x32_bf16 v[98:101], v[172:175], v[194:197], v[98:101]
	v_mfma_f32_16x16x32_bf16 v[88:91], v[164:167], v[202:205], v[88:91]
	v_mfma_f32_16x16x32_bf16 v[80:83], v[172:175], v[202:205], v[80:83]
	v_mfma_f32_16x16x32_bf16 v[72:75], v[164:167], v[210:213], v[72:75]
	v_mfma_f32_16x16x32_bf16 v[64:67], v[172:175], v[210:213], v[64:67]
	s_setprio 0
	s_barrier
	s_add_i32 s18, s35, s47
	s_mov_b32 m0, s18
	ds_read_b128 v[176:179], v155 offset:16384
	ds_read_b128 v[180:183], v155 offset:17408
	ds_read_b128 v[190:193], v155 offset:18432
	ds_read_b128 v[194:197], v155 offset:19456
	ds_read_b128 v[198:201], v155 offset:20480
	ds_read_b128 v[202:205], v155 offset:21504
	ds_read_b128 v[206:209], v155 offset:22528
	ds_read_b128 v[210:213], v155 offset:23552
	global_load_lds_dwordx4 v134, s[44:45]
	s_add_i32 m0, s18, 0x2000
	s_add_u32 s18, s44, 0x40000
	s_addc_u32 s19, s45, 0
	s_add_i32 s35, s49, s47
	global_load_lds_dwordx4 v130, s[44:45]
	s_mov_b32 m0, s35
	s_nop 0
	global_load_lds_dwordx4 v134, s[18:19]
	s_add_i32 m0, s35, 0x2000
	s_nop 0
	global_load_lds_dwordx4 v130, s[18:19]
	s_waitcnt vmcnt(6)
	s_waitcnt lgkmcnt(0)
	s_barrier
	s_setprio 1
	s_waitcnt lgkmcnt(0)
	v_mfma_f32_16x16x32_bf16 v[60:63], v[138:141], v[176:179], 0
	v_mfma_f32_16x16x32_bf16 v[52:55], v[146:149], v[176:179], 0
	v_mfma_f32_16x16x32_bf16 v[44:47], v[138:141], v[190:193], 0
	v_mfma_f32_16x16x32_bf16 v[36:39], v[146:149], v[190:193], 0
	v_mfma_f32_16x16x32_bf16 v[28:31], v[138:141], v[198:201], 0
	v_mfma_f32_16x16x32_bf16 v[20:23], v[146:149], v[198:201], 0
	v_mfma_f32_16x16x32_bf16 v[12:15], v[138:141], v[206:209], 0
	v_mfma_f32_16x16x32_bf16 v[4:7], v[146:149], v[206:209], 0
	v_mfma_f32_16x16x32_bf16 v[60:63], v[142:145], v[180:183], v[60:63]
	v_mfma_f32_16x16x32_bf16 v[52:55], v[156:159], v[180:183], v[52:55]
	v_mfma_f32_16x16x32_bf16 v[44:47], v[142:145], v[194:197], v[44:47]
	v_mfma_f32_16x16x32_bf16 v[36:39], v[156:159], v[194:197], v[36:39]
	v_mfma_f32_16x16x32_bf16 v[28:31], v[142:145], v[202:205], v[28:31]
	v_mfma_f32_16x16x32_bf16 v[20:23], v[156:159], v[202:205], v[20:23]
	v_mfma_f32_16x16x32_bf16 v[12:15], v[142:145], v[210:213], v[12:15]
	v_mfma_f32_16x16x32_bf16 v[4:7], v[156:159], v[210:213], v[4:7]
	v_mfma_f32_16x16x32_bf16 v[56:59], v[160:163], v[176:179], 0
	v_mfma_f32_16x16x32_bf16 v[48:51], v[168:171], v[176:179], 0
	v_mfma_f32_16x16x32_bf16 v[40:43], v[160:163], v[190:193], 0
	v_mfma_f32_16x16x32_bf16 v[32:35], v[168:171], v[190:193], 0
	v_mfma_f32_16x16x32_bf16 v[24:27], v[160:163], v[198:201], 0
	v_mfma_f32_16x16x32_bf16 v[16:19], v[168:171], v[198:201], 0
	v_mfma_f32_16x16x32_bf16 v[8:11], v[160:163], v[206:209], 0
	v_mfma_f32_16x16x32_bf16 v[0:3], v[168:171], v[206:209], 0
	v_mfma_f32_16x16x32_bf16 v[56:59], v[164:167], v[180:183], v[56:59]
	v_mfma_f32_16x16x32_bf16 v[48:51], v[172:175], v[180:183], v[48:51]
	v_mfma_f32_16x16x32_bf16 v[40:43], v[164:167], v[194:197], v[40:43]
	v_mfma_f32_16x16x32_bf16 v[32:35], v[172:175], v[194:197], v[32:35]
	v_mfma_f32_16x16x32_bf16 v[24:27], v[164:167], v[202:205], v[24:27]
	v_mfma_f32_16x16x32_bf16 v[16:19], v[172:175], v[202:205], v[16:19]
	v_mfma_f32_16x16x32_bf16 v[8:11], v[164:167], v[210:213], v[8:11]
	v_mfma_f32_16x16x32_bf16 v[0:3], v[172:175], v[210:213], v[0:3]
	s_setprio 0
	s_barrier
	s_add_i32 s35, 0, 0x18000
	v_add_u32_e32 v96, s35, v151
	s_add_i32 s44, 0, 0x1c000
	ds_read_b128 v[138:141], v96
	ds_read_b128 v[142:145], v96 offset:1024
	ds_read_b128 v[146:149], v96 offset:2048
	ds_read_b128 v[156:159], v96 offset:3072
	v_add_u32_e32 v96, s44, v151
	ds_read_b128 v[160:163], v96
	ds_read_b128 v[164:167], v96 offset:1024
	ds_read_b128 v[168:171], v96 offset:2048
	ds_read_b128 v[172:175], v96 offset:3072
	s_mov_b32 m0, s65
	s_nop 0
	global_load_lds_dwordx4 v136, s[42:43]
	s_mov_b32 m0, s72
	s_nop 0
	global_load_lds_dwordx4 v132, s[42:43]
	s_add_u32 s18, s42, 0x40000
	s_addc_u32 s19, s43, 0
	s_mov_b32 m0, s73
	ds_read_b128 v[176:179], v155 offset:32768
	ds_read_b128 v[180:183], v155 offset:33792
	ds_read_b128 v[190:193], v155 offset:34816
	ds_read_b128 v[194:197], v155 offset:35840
	ds_read_b128 v[198:201], v155 offset:36864
	ds_read_b128 v[202:205], v155 offset:37888
	ds_read_b128 v[206:209], v155 offset:38912
	ds_read_b128 v[210:213], v155 offset:39936
	global_load_lds_dwordx4 v136, s[18:19]
	s_mov_b32 m0, s74
	s_nop 0
	global_load_lds_dwordx4 v132, s[18:19]
	s_waitcnt vmcnt(8)
	s_waitcnt lgkmcnt(0)
	s_barrier
	s_setprio 1
	s_waitcnt lgkmcnt(0)
	v_mfma_f32_16x16x32_bf16 v[126:129], v[138:141], v[176:179], v[126:129]
	v_mfma_f32_16x16x32_bf16 v[118:121], v[146:149], v[176:179], v[118:121]
	v_mfma_f32_16x16x32_bf16 v[110:113], v[138:141], v[190:193], v[110:113]
	v_mfma_f32_16x16x32_bf16 v[102:105], v[146:149], v[190:193], v[102:105]
	v_mfma_f32_16x16x32_bf16 v[92:95], v[138:141], v[198:201], v[92:95]
	v_mfma_f32_16x16x32_bf16 v[84:87], v[146:149], v[198:201], v[84:87]
	v_mfma_f32_16x16x32_bf16 v[76:79], v[138:141], v[206:209], v[76:79]
	v_mfma_f32_16x16x32_bf16 v[68:71], v[146:149], v[206:209], v[68:71]
	v_mfma_f32_16x16x32_bf16 v[126:129], v[142:145], v[180:183], v[126:129]
	v_mfma_f32_16x16x32_bf16 v[118:121], v[156:159], v[180:183], v[118:121]
	v_mfma_f32_16x16x32_bf16 v[110:113], v[142:145], v[194:197], v[110:113]
	v_mfma_f32_16x16x32_bf16 v[102:105], v[156:159], v[194:197], v[102:105]
	v_mfma_f32_16x16x32_bf16 v[92:95], v[142:145], v[202:205], v[92:95]
	v_mfma_f32_16x16x32_bf16 v[84:87], v[156:159], v[202:205], v[84:87]
	v_mfma_f32_16x16x32_bf16 v[76:79], v[142:145], v[210:213], v[76:79]
	v_mfma_f32_16x16x32_bf16 v[68:71], v[156:159], v[210:213], v[68:71]
	v_mfma_f32_16x16x32_bf16 v[122:125], v[160:163], v[176:179], v[122:125]
	v_mfma_f32_16x16x32_bf16 v[114:117], v[168:171], v[176:179], v[114:117]
	v_mfma_f32_16x16x32_bf16 v[106:109], v[160:163], v[190:193], v[106:109]
	v_mfma_f32_16x16x32_bf16 v[98:101], v[168:171], v[190:193], v[98:101]
	v_mfma_f32_16x16x32_bf16 v[88:91], v[160:163], v[198:201], v[88:91]
	v_mfma_f32_16x16x32_bf16 v[80:83], v[168:171], v[198:201], v[80:83]
	v_mfma_f32_16x16x32_bf16 v[72:75], v[160:163], v[206:209], v[72:75]
	v_mfma_f32_16x16x32_bf16 v[64:67], v[168:171], v[206:209], v[64:67]
	v_mfma_f32_16x16x32_bf16 v[122:125], v[164:167], v[180:183], v[122:125]
	v_mfma_f32_16x16x32_bf16 v[114:117], v[172:175], v[180:183], v[114:117]
	v_mfma_f32_16x16x32_bf16 v[106:109], v[164:167], v[194:197], v[106:109]
	v_mfma_f32_16x16x32_bf16 v[98:101], v[172:175], v[194:197], v[98:101]
	v_mfma_f32_16x16x32_bf16 v[88:91], v[164:167], v[202:205], v[88:91]
	v_mfma_f32_16x16x32_bf16 v[80:83], v[172:175], v[202:205], v[80:83]
	v_mfma_f32_16x16x32_bf16 v[72:75], v[164:167], v[210:213], v[72:75]
	v_mfma_f32_16x16x32_bf16 v[64:67], v[172:175], v[210:213], v[64:67]
	s_setprio 0
	s_barrier
	s_add_i32 s18, s35, s47
	s_mov_b32 m0, s18
	ds_read_b128 v[176:179], v155 offset:49152
	ds_read_b128 v[180:183], v155 offset:50176
	ds_read_b128 v[190:193], v155 offset:51200
	ds_read_b128 v[194:197], v155 offset:52224
	ds_read_b128 v[198:201], v155 offset:53248
	ds_read_b128 v[202:205], v155 offset:54272
	ds_read_b128 v[206:209], v155 offset:55296
	ds_read_b128 v[210:213], v155 offset:56320
	global_load_lds_dwordx4 v134, s[68:69]
	s_add_i32 m0, s18, 0x2000
	s_add_u32 s18, s68, 0x40000
	s_addc_u32 s19, s69, 0
	s_add_i32 s35, s44, s47
	global_load_lds_dwordx4 v130, s[68:69]
	s_mov_b32 m0, s35
	s_nop 0
	global_load_lds_dwordx4 v134, s[18:19]
	s_add_i32 m0, s35, 0x2000
	s_nop 0
	global_load_lds_dwordx4 v130, s[18:19]
	s_waitcnt vmcnt(6)
	s_waitcnt lgkmcnt(0)
	s_barrier
	s_setprio 1
	s_waitcnt lgkmcnt(0)
	v_mfma_f32_16x16x32_bf16 v[60:63], v[138:141], v[176:179], v[60:63]
	v_mfma_f32_16x16x32_bf16 v[52:55], v[146:149], v[176:179], v[52:55]
	v_mfma_f32_16x16x32_bf16 v[44:47], v[138:141], v[190:193], v[44:47]
	v_mfma_f32_16x16x32_bf16 v[36:39], v[146:149], v[190:193], v[36:39]
	v_mfma_f32_16x16x32_bf16 v[28:31], v[138:141], v[198:201], v[28:31]
	v_mfma_f32_16x16x32_bf16 v[20:23], v[146:149], v[198:201], v[20:23]
	v_mfma_f32_16x16x32_bf16 v[12:15], v[138:141], v[206:209], v[12:15]
	v_mfma_f32_16x16x32_bf16 v[4:7], v[146:149], v[206:209], v[4:7]
	v_mfma_f32_16x16x32_bf16 v[60:63], v[142:145], v[180:183], v[60:63]
	v_mfma_f32_16x16x32_bf16 v[52:55], v[156:159], v[180:183], v[52:55]
	v_mfma_f32_16x16x32_bf16 v[44:47], v[142:145], v[194:197], v[44:47]
	v_mfma_f32_16x16x32_bf16 v[36:39], v[156:159], v[194:197], v[36:39]
	v_mfma_f32_16x16x32_bf16 v[28:31], v[142:145], v[202:205], v[28:31]
	v_mfma_f32_16x16x32_bf16 v[20:23], v[156:159], v[202:205], v[20:23]
	v_mfma_f32_16x16x32_bf16 v[12:15], v[142:145], v[210:213], v[12:15]
	v_mfma_f32_16x16x32_bf16 v[4:7], v[156:159], v[210:213], v[4:7]
	v_mfma_f32_16x16x32_bf16 v[56:59], v[160:163], v[176:179], v[56:59]
	v_mfma_f32_16x16x32_bf16 v[48:51], v[168:171], v[176:179], v[48:51]
	v_mfma_f32_16x16x32_bf16 v[40:43], v[160:163], v[190:193], v[40:43]
	v_mfma_f32_16x16x32_bf16 v[32:35], v[168:171], v[190:193], v[32:35]
	v_mfma_f32_16x16x32_bf16 v[24:27], v[160:163], v[198:201], v[24:27]
	v_mfma_f32_16x16x32_bf16 v[16:19], v[168:171], v[198:201], v[16:19]
	v_mfma_f32_16x16x32_bf16 v[8:11], v[160:163], v[206:209], v[8:11]
	v_mfma_f32_16x16x32_bf16 v[0:3], v[168:171], v[206:209], v[0:3]
	v_mfma_f32_16x16x32_bf16 v[56:59], v[164:167], v[180:183], v[56:59]
	v_mfma_f32_16x16x32_bf16 v[48:51], v[172:175], v[180:183], v[48:51]
	v_mfma_f32_16x16x32_bf16 v[40:43], v[164:167], v[194:197], v[40:43]
	v_mfma_f32_16x16x32_bf16 v[32:35], v[172:175], v[194:197], v[32:35]
	v_mfma_f32_16x16x32_bf16 v[24:27], v[164:167], v[202:205], v[24:27]
	v_mfma_f32_16x16x32_bf16 v[16:19], v[172:175], v[202:205], v[16:19]
	v_mfma_f32_16x16x32_bf16 v[8:11], v[164:167], v[210:213], v[8:11]
	v_mfma_f32_16x16x32_bf16 v[0:3], v[172:175], v[210:213], v[0:3]
	s_setprio 0
	s_barrier
	s_add_i32 s85, s85, 2
	s_add_u32 s83, s83, 0x100
	s_addc_u32 s84, s84, 0
	s_cmp_gt_u32 s85, 13
	s_cbranch_scc0 .LBB0_740
.LBB0_740:
	s_add_u32 s18, s66, 0x80
	s_addc_u32 s19, s67, 0
	s_add_u32 s66, s66, 0x100
	s_addc_u32 s67, s67, 0
	s_cmp_eq_u32 s85, 12
	s_cselect_b32 s42, s81, s66
	s_cselect_b32 s43, s59, s67
	s_cselect_b32 s45, s31, s84
	s_cselect_b32 s44, s82, s83
	s_add_u32 s68, s44, 0x80
	s_addc_u32 s69, s45, 0
	s_add_i32 s35, 0, 0x10000
	s_add_i32 s49, 0, 0x14000
	v_add_u32_e32 v96, s35, v151
	v_add_u32_e32 v150, s49, v151
	ds_read_b128 v[138:141], v96
	ds_read_b128 v[142:145], v96 offset:1024
	ds_read_b128 v[146:149], v96 offset:2048
	ds_read_b128 v[156:159], v96 offset:3072
	ds_read_b128 v[160:163], v150
	ds_read_b128 v[164:167], v150 offset:1024
	ds_read_b128 v[168:171], v150 offset:2048
	ds_read_b128 v[172:175], v150 offset:3072
	s_mov_b32 m0, s77
	ds_read_b128 v[176:179], v155
	ds_read_b128 v[180:183], v155 offset:1024
	ds_read_b128 v[190:193], v155 offset:2048
	ds_read_b128 v[194:197], v155 offset:3072
	ds_read_b128 v[198:201], v155 offset:4096
	ds_read_b128 v[202:205], v155 offset:5120
	ds_read_b128 v[206:209], v155 offset:6144
	ds_read_b128 v[210:213], v155 offset:7168
	global_load_lds_dwordx4 v136, s[18:19]
	s_mov_b32 m0, s78
	s_nop 0
	global_load_lds_dwordx4 v132, s[18:19]
	s_add_u32 s18, s18, 0x40000
	s_addc_u32 s19, s19, 0
	s_add_i32 m0, s65, 0xc000
	s_nop 0
	global_load_lds_dwordx4 v136, s[18:19]
	s_add_i32 m0, s65, 0xe000
	s_nop 0
	global_load_lds_dwordx4 v132, s[18:19]
	s_waitcnt vmcnt(8)
	s_waitcnt lgkmcnt(0)
	s_barrier
	s_setprio 1
	s_waitcnt lgkmcnt(0)
	v_mfma_f32_16x16x32_bf16 v[126:129], v[138:141], v[176:179], v[126:129]
	v_mfma_f32_16x16x32_bf16 v[118:121], v[146:149], v[176:179], v[118:121]
	v_mfma_f32_16x16x32_bf16 v[110:113], v[138:141], v[190:193], v[110:113]
	v_mfma_f32_16x16x32_bf16 v[102:105], v[146:149], v[190:193], v[102:105]
	v_mfma_f32_16x16x32_bf16 v[92:95], v[138:141], v[198:201], v[92:95]
	v_mfma_f32_16x16x32_bf16 v[84:87], v[146:149], v[198:201], v[84:87]
	v_mfma_f32_16x16x32_bf16 v[76:79], v[138:141], v[206:209], v[76:79]
	v_mfma_f32_16x16x32_bf16 v[68:71], v[146:149], v[206:209], v[68:71]
	v_mfma_f32_16x16x32_bf16 v[126:129], v[142:145], v[180:183], v[126:129]
	v_mfma_f32_16x16x32_bf16 v[118:121], v[156:159], v[180:183], v[118:121]
	v_mfma_f32_16x16x32_bf16 v[110:113], v[142:145], v[194:197], v[110:113]
	v_mfma_f32_16x16x32_bf16 v[102:105], v[156:159], v[194:197], v[102:105]
	v_mfma_f32_16x16x32_bf16 v[92:95], v[142:145], v[202:205], v[92:95]
	v_mfma_f32_16x16x32_bf16 v[84:87], v[156:159], v[202:205], v[84:87]
	v_mfma_f32_16x16x32_bf16 v[76:79], v[142:145], v[210:213], v[76:79]
	v_mfma_f32_16x16x32_bf16 v[68:71], v[156:159], v[210:213], v[68:71]
	v_mfma_f32_16x16x32_bf16 v[122:125], v[160:163], v[176:179], v[122:125]
	v_mfma_f32_16x16x32_bf16 v[114:117], v[168:171], v[176:179], v[114:117]
	v_mfma_f32_16x16x32_bf16 v[106:109], v[160:163], v[190:193], v[106:109]
	v_mfma_f32_16x16x32_bf16 v[98:101], v[168:171], v[190:193], v[98:101]
	v_mfma_f32_16x16x32_bf16 v[88:91], v[160:163], v[198:201], v[88:91]
	v_mfma_f32_16x16x32_bf16 v[80:83], v[168:171], v[198:201], v[80:83]
	v_mfma_f32_16x16x32_bf16 v[72:75], v[160:163], v[206:209], v[72:75]
	v_mfma_f32_16x16x32_bf16 v[64:67], v[168:171], v[206:209], v[64:67]
	v_mfma_f32_16x16x32_bf16 v[122:125], v[164:167], v[180:183], v[122:125]
	v_mfma_f32_16x16x32_bf16 v[114:117], v[172:175], v[180:183], v[114:117]
	v_mfma_f32_16x16x32_bf16 v[106:109], v[164:167], v[194:197], v[106:109]
	v_mfma_f32_16x16x32_bf16 v[98:101], v[172:175], v[194:197], v[98:101]
	v_mfma_f32_16x16x32_bf16 v[88:91], v[164:167], v[202:205], v[88:91]
	v_mfma_f32_16x16x32_bf16 v[80:83], v[172:175], v[202:205], v[80:83]
	v_mfma_f32_16x16x32_bf16 v[72:75], v[164:167], v[210:213], v[72:75]
	v_mfma_f32_16x16x32_bf16 v[64:67], v[172:175], v[210:213], v[64:67]
	s_setprio 0
	s_barrier
	s_add_i32 s18, s35, s47
	s_mov_b32 m0, s18
	ds_read_b128 v[176:179], v155 offset:16384
	ds_read_b128 v[180:183], v155 offset:17408
	ds_read_b128 v[190:193], v155 offset:18432
	ds_read_b128 v[194:197], v155 offset:19456
	ds_read_b128 v[198:201], v155 offset:20480
	ds_read_b128 v[202:205], v155 offset:21504
	ds_read_b128 v[206:209], v155 offset:22528
	ds_read_b128 v[210:213], v155 offset:23552
	global_load_lds_dwordx4 v134, s[44:45]
	s_add_i32 m0, s18, 0x2000
	s_add_u32 s18, s44, 0x40000
	s_addc_u32 s19, s45, 0
	s_add_i32 s35, s49, s47
	global_load_lds_dwordx4 v130, s[44:45]
	s_mov_b32 m0, s35
	s_nop 0
	global_load_lds_dwordx4 v134, s[18:19]
	s_add_i32 m0, s35, 0x2000
	s_nop 0
	global_load_lds_dwordx4 v130, s[18:19]
	s_waitcnt vmcnt(6)
	s_waitcnt lgkmcnt(0)
	s_barrier
	s_setprio 1
	s_waitcnt lgkmcnt(0)
	v_mfma_f32_16x16x32_bf16 v[60:63], v[138:141], v[176:179], v[60:63]
	v_mfma_f32_16x16x32_bf16 v[52:55], v[146:149], v[176:179], v[52:55]
	v_mfma_f32_16x16x32_bf16 v[44:47], v[138:141], v[190:193], v[44:47]
	v_mfma_f32_16x16x32_bf16 v[36:39], v[146:149], v[190:193], v[36:39]
	v_mfma_f32_16x16x32_bf16 v[28:31], v[138:141], v[198:201], v[28:31]
	v_mfma_f32_16x16x32_bf16 v[20:23], v[146:149], v[198:201], v[20:23]
	v_mfma_f32_16x16x32_bf16 v[12:15], v[138:141], v[206:209], v[12:15]
	v_mfma_f32_16x16x32_bf16 v[4:7], v[146:149], v[206:209], v[4:7]
	v_mfma_f32_16x16x32_bf16 v[60:63], v[142:145], v[180:183], v[60:63]
	v_mfma_f32_16x16x32_bf16 v[52:55], v[156:159], v[180:183], v[52:55]
	v_mfma_f32_16x16x32_bf16 v[44:47], v[142:145], v[194:197], v[44:47]
	v_mfma_f32_16x16x32_bf16 v[36:39], v[156:159], v[194:197], v[36:39]
	v_mfma_f32_16x16x32_bf16 v[28:31], v[142:145], v[202:205], v[28:31]
	v_mfma_f32_16x16x32_bf16 v[20:23], v[156:159], v[202:205], v[20:23]
	v_mfma_f32_16x16x32_bf16 v[12:15], v[142:145], v[210:213], v[12:15]
	v_mfma_f32_16x16x32_bf16 v[4:7], v[156:159], v[210:213], v[4:7]
	v_mfma_f32_16x16x32_bf16 v[56:59], v[160:163], v[176:179], v[56:59]
	v_mfma_f32_16x16x32_bf16 v[48:51], v[168:171], v[176:179], v[48:51]
	v_mfma_f32_16x16x32_bf16 v[40:43], v[160:163], v[190:193], v[40:43]
	v_mfma_f32_16x16x32_bf16 v[32:35], v[168:171], v[190:193], v[32:35]
	v_mfma_f32_16x16x32_bf16 v[24:27], v[160:163], v[198:201], v[24:27]
	v_mfma_f32_16x16x32_bf16 v[16:19], v[168:171], v[198:201], v[16:19]
	v_mfma_f32_16x16x32_bf16 v[8:11], v[160:163], v[206:209], v[8:11]
	v_mfma_f32_16x16x32_bf16 v[0:3], v[168:171], v[206:209], v[0:3]
	v_mfma_f32_16x16x32_bf16 v[56:59], v[164:167], v[180:183], v[56:59]
	v_mfma_f32_16x16x32_bf16 v[48:51], v[172:175], v[180:183], v[48:51]
	v_mfma_f32_16x16x32_bf16 v[40:43], v[164:167], v[194:197], v[40:43]
	v_mfma_f32_16x16x32_bf16 v[32:35], v[172:175], v[194:197], v[32:35]
	v_mfma_f32_16x16x32_bf16 v[24:27], v[164:167], v[202:205], v[24:27]
	v_mfma_f32_16x16x32_bf16 v[16:19], v[172:175], v[202:205], v[16:19]
	v_mfma_f32_16x16x32_bf16 v[8:11], v[164:167], v[210:213], v[8:11]
	v_mfma_f32_16x16x32_bf16 v[0:3], v[172:175], v[210:213], v[0:3]
	s_setprio 0
	s_barrier
	s_add_i32 s35, 0, 0x18000
	v_add_u32_e32 v96, s35, v151
	s_add_i32 s44, 0, 0x1c000
	ds_read_b128 v[138:141], v96
	ds_read_b128 v[142:145], v96 offset:1024
	ds_read_b128 v[146:149], v96 offset:2048
	ds_read_b128 v[156:159], v96 offset:3072
	v_add_u32_e32 v96, s44, v151
	ds_read_b128 v[160:163], v96
	ds_read_b128 v[164:167], v96 offset:1024
	ds_read_b128 v[168:171], v96 offset:2048
	ds_read_b128 v[172:175], v96 offset:3072
	s_mov_b32 m0, s65
	s_nop 0
	global_load_lds_dwordx4 v136, s[42:43]
	s_mov_b32 m0, s72
	s_nop 0
	global_load_lds_dwordx4 v132, s[42:43]
	s_add_u32 s18, s42, 0x40000
	s_addc_u32 s19, s43, 0
	s_mov_b32 m0, s73
	ds_read_b128 v[176:179], v155 offset:32768
	ds_read_b128 v[180:183], v155 offset:33792
	ds_read_b128 v[190:193], v155 offset:34816
	ds_read_b128 v[194:197], v155 offset:35840
	ds_read_b128 v[198:201], v155 offset:36864
	ds_read_b128 v[202:205], v155 offset:37888
	ds_read_b128 v[206:209], v155 offset:38912
	ds_read_b128 v[210:213], v155 offset:39936
	global_load_lds_dwordx4 v136, s[18:19]
	s_mov_b32 m0, s74
	s_nop 0
	global_load_lds_dwordx4 v132, s[18:19]
	s_waitcnt vmcnt(8)
	s_waitcnt lgkmcnt(0)
	s_barrier
	s_setprio 1
	s_waitcnt lgkmcnt(0)
	v_mfma_f32_16x16x32_bf16 v[126:129], v[138:141], v[176:179], v[126:129]
	v_mfma_f32_16x16x32_bf16 v[118:121], v[146:149], v[176:179], v[118:121]
	v_mfma_f32_16x16x32_bf16 v[110:113], v[138:141], v[190:193], v[110:113]
	v_mfma_f32_16x16x32_bf16 v[102:105], v[146:149], v[190:193], v[102:105]
	v_mfma_f32_16x16x32_bf16 v[92:95], v[138:141], v[198:201], v[92:95]
	v_mfma_f32_16x16x32_bf16 v[84:87], v[146:149], v[198:201], v[84:87]
	v_mfma_f32_16x16x32_bf16 v[76:79], v[138:141], v[206:209], v[76:79]
	v_mfma_f32_16x16x32_bf16 v[68:71], v[146:149], v[206:209], v[68:71]
	v_mfma_f32_16x16x32_bf16 v[126:129], v[142:145], v[180:183], v[126:129]
	v_mfma_f32_16x16x32_bf16 v[118:121], v[156:159], v[180:183], v[118:121]
	v_mfma_f32_16x16x32_bf16 v[110:113], v[142:145], v[194:197], v[110:113]
	v_mfma_f32_16x16x32_bf16 v[102:105], v[156:159], v[194:197], v[102:105]
	v_mfma_f32_16x16x32_bf16 v[92:95], v[142:145], v[202:205], v[92:95]
	v_mfma_f32_16x16x32_bf16 v[84:87], v[156:159], v[202:205], v[84:87]
	v_mfma_f32_16x16x32_bf16 v[76:79], v[142:145], v[210:213], v[76:79]
	v_mfma_f32_16x16x32_bf16 v[68:71], v[156:159], v[210:213], v[68:71]
	v_mfma_f32_16x16x32_bf16 v[122:125], v[160:163], v[176:179], v[122:125]
	v_mfma_f32_16x16x32_bf16 v[114:117], v[168:171], v[176:179], v[114:117]
	v_mfma_f32_16x16x32_bf16 v[106:109], v[160:163], v[190:193], v[106:109]
	v_mfma_f32_16x16x32_bf16 v[98:101], v[168:171], v[190:193], v[98:101]
	v_mfma_f32_16x16x32_bf16 v[88:91], v[160:163], v[198:201], v[88:91]
	v_mfma_f32_16x16x32_bf16 v[80:83], v[168:171], v[198:201], v[80:83]
	v_mfma_f32_16x16x32_bf16 v[72:75], v[160:163], v[206:209], v[72:75]
	v_mfma_f32_16x16x32_bf16 v[64:67], v[168:171], v[206:209], v[64:67]
	v_mfma_f32_16x16x32_bf16 v[122:125], v[164:167], v[180:183], v[122:125]
	v_mfma_f32_16x16x32_bf16 v[114:117], v[172:175], v[180:183], v[114:117]
	v_mfma_f32_16x16x32_bf16 v[106:109], v[164:167], v[194:197], v[106:109]
	v_mfma_f32_16x16x32_bf16 v[98:101], v[172:175], v[194:197], v[98:101]
	v_mfma_f32_16x16x32_bf16 v[88:91], v[164:167], v[202:205], v[88:91]
	v_mfma_f32_16x16x32_bf16 v[80:83], v[172:175], v[202:205], v[80:83]
	v_mfma_f32_16x16x32_bf16 v[72:75], v[164:167], v[210:213], v[72:75]
	v_mfma_f32_16x16x32_bf16 v[64:67], v[172:175], v[210:213], v[64:67]
	s_setprio 0
	s_barrier
	s_add_i32 s18, s35, s47
	s_mov_b32 m0, s18
	ds_read_b128 v[176:179], v155 offset:49152
	ds_read_b128 v[180:183], v155 offset:50176
	ds_read_b128 v[190:193], v155 offset:51200
	ds_read_b128 v[194:197], v155 offset:52224
	ds_read_b128 v[198:201], v155 offset:53248
	ds_read_b128 v[202:205], v155 offset:54272
	ds_read_b128 v[206:209], v155 offset:55296
	ds_read_b128 v[210:213], v155 offset:56320
	global_load_lds_dwordx4 v134, s[68:69]
	s_add_i32 m0, s18, 0x2000
	s_add_u32 s18, s68, 0x40000
	s_addc_u32 s19, s69, 0
	s_add_i32 s35, s44, s47
	global_load_lds_dwordx4 v130, s[68:69]
	s_mov_b32 m0, s35
	s_nop 0
	global_load_lds_dwordx4 v134, s[18:19]
	s_add_i32 m0, s35, 0x2000
	s_nop 0
	global_load_lds_dwordx4 v130, s[18:19]
	s_waitcnt vmcnt(6)
	s_cmp_lg_u32 s85, 12
	s_cbranch_scc1 .Lswi_ssq_skip
	global_load_dwordx4 v[220:223], v[252:253], off
	global_load_dwordx4 v[224:227], v[252:253], off offset:1024
	global_load_dwordx4 v[228:231], v[252:253], off offset:2048
	global_load_dwordx4 v[232:235], v[252:253], off offset:3072
	global_load_dwordx4 v[236:239], v[184:185], off
	global_load_dwordx4 v[240:243], v[184:185], off offset:1024
	global_load_dwordx4 v[244:247], v[184:185], off offset:2048
	global_load_dwordx4 v[248:251], v[184:185], off offset:3072
